# aligned combo12 with arrival-rank-based background conversion: the first 26 arrivers per XCC share each barrier's items, the last six convert nothing
# speedup vs baseline: 1.0015x; 1.0015x over previous
; __device__ __forceinline__ unsigned xb_add(unsigned* p, unsigned v) { return __hip_atomic_fetch_add(p, v, __ATOMIC_RELAXED, __HIP_MEMORY_SCOPE_AGENT); }
; __device__ __forceinline__ void xcd_barrier_thread0(const XcdBarrier& b) {
;     ...
;         const unsigned old = xb_add(&bar[XB_XSUB(b.x)], 1u);
;         const unsigned gen = old / nloc;
;         if (old + 1u == (gen + 1u) * nloc) {
.LBB0_721:
	s_or_b64 exec, exec, s[0:1]
	v_cvt_f32_u32_e32 v7, v5
	s_waitcnt vmcnt(0)
	v_readfirstlane_b32 s0, v6
	s_and_b32 s8, s0, 31
	s_add_i32 s9, s90, 1
	s_lshl_b32 s9, s9, 8
	s_or_b32 s8, s8, s9
	v_mov_b32_e32 v20, 0x20180
	v_mov_b32_e32 v21, s8
	ds_write_b32 v20, v21
	v_sub_u32_e32 v6, 0, v5
	v_rcp_iflag_f32_e32 v7, v7
	v_add_u32_e32 v8, s0, v2
	v_mul_f32_e32 v7, 0x4f7ffffe, v7
	v_cvt_u32_f32_e32 v7, v7
	v_mul_lo_u32 v2, v6, v7
	v_mul_hi_u32 v2, v7, v2
	v_add_u32_e32 v2, v7, v2
	v_mul_hi_u32 v2, v8, v2
	v_mul_lo_u32 v6, v2, v5
	v_sub_u32_e32 v6, v8, v6
	v_add_u32_e32 v7, 1, v2
	v_cmp_ge_u32_e32 vcc, v6, v5
	s_nop 1
	v_cndmask_b32_e32 v2, v2, v7, vcc
	v_sub_u32_e32 v7, v6, v5
	v_cndmask_b32_e32 v6, v6, v7, vcc
	v_add_u32_e32 v7, 1, v2
	v_cmp_ge_u32_e32 vcc, v6, v5
	v_add_u32_e32 v6, 1, v8
	s_nop 0
	v_cndmask_b32_e32 v2, v2, v7, vcc
	v_mul_lo_u32 v7, v5, v2
	v_add_u32_e32 v5, v7, v5
	v_cmp_ne_u32_e32 vcc, v6, v5
	s_and_saveexec_b64 s[0:1], vcc
	s_xor_b64 s[0:1], exec, s[0:1]
	s_cbranch_execz .LBB0_735
	v_readlane_b32 s8, v253, 14
	v_readlane_b32 s9, v253, 15
	s_waitcnt lgkmcnt(0)
	s_nop 3
	buffer_inv sc1
	global_load_dword v4, v3, s[8:9] sc1
	s_waitcnt vmcnt(0)
	v_cmp_eq_u32_e32 vcc, v4, v2
	s_and_saveexec_b64 s[8:9], vcc
	s_cbranch_execz .LBB0_734
	s_mov_b32 s15, 1
	s_mov_b64 s[12:13], 0
	s_branch .LBB0_725

; __device__ __forceinline__ void xcd_barrier_cv(const XcdBarrier& b, Frame& F, const CvPtrs& P, int s, bool local) {
;     asm volatile("s_waitcnt vmcnt(0)" ::: "memory");
;     __syncthreads();
;     if (threadIdx.x < 64) { if (threadIdx.x == 0) { if (local) xcc_barrier_thread0(b); else xcd_barrier_thread0(b); } }
;     else if (cv_bg_share(s) >= 0 && cv_bg_share(s) < CV_BG_SHARES) cv_background(F, P, s);
.LBB0_769:
	s_and_b64 vcc, exec, s[0:1]
	s_cbranch_vccz .LBB0_1015
	s_sleep 64
	s_sleep 64
	v_mov_b32_e32 v20, 0x20180
	s_add_i32 s7, s90, 1
	s_movk_i32 s4, 0x800
.Lbgr_wait:
	ds_read_b32 v21, v20
	s_waitcnt lgkmcnt(0)
	v_readfirstlane_b32 s9, v21
	s_lshr_b32 s8, s9, 8
	s_cmp_eq_u32 s8, s7
	s_cbranch_scc1 .Lbgr_ok
	s_sleep 2
	s_sub_u32 s4, s4, 1
	s_cmp_lg_u32 s4, 0
	s_cbranch_scc1 .Lbgr_wait
	s_movk_i32 s9, 0x40
.Lbgr_ok:
	s_and_b32 s9, s9, 0x7f
	v_writelane_b32 v255, s9, 20
	v_mov_b32_e32 v4, v0
	s_mov_b64 s[6:7], -1
	v_readfirstlane_b32 s8, v4
	s_mov_b64 s[0:1], 0
	s_cmp_lt_i32 s89, 5
	s_mov_b64 s[4:5], 0
	s_cbranch_scc1 .LBB0_787
	s_cmp_gt_i32 s89, 7
	s_cbranch_scc0 .LBB0_779
	s_cmp_gt_i32 s89, 8
	s_cbranch_scc0 .LBB0_776
	s_cmp_eq_u32 s89, 9
	s_mov_b64 s[4:5], -1
	s_cbranch_scc0 .LBB0_775
	s_mov_b64 s[4:5], 0

; #define LAS __attribute__((address_space(3)))
; __device__ __forceinline__ void cv_background(Frame& F, const CvPtrs& P, int s) {
;     ...
;     const int w = __builtin_amdgcn_readfirstlane(tv >> 6) - 1, lane = tv & 63, nbw = F.G * (NWAVES - 1);
;     LAS float* scr = (LAS float*)(F.lds + RING_OFF + (w + 1) * 16384);
;     const int sh_ = cv_bg_share(s), hi = (sh_ + 1) * CV_BG_PER < CV_BG_TOTAL ? (sh_ + 1) * CV_BG_PER : CV_BG_TOTAL;
;     for (int j = sh_ * CV_BG_PER + F.vcu * (NWAVES - 1) + w; j < hi; j += nbw) {
.Lbg_up:
	s_lshl_b32 s4, s4, 3
	s_add_u32 s4, s4, s5
	s_cmpk_lt_u32 s4, 0xc2
	s_cbranch_scc1 .LBB0_1015
	s_sub_u32 s98, s4, 0xc2
	s_movk_i32 s99, 0x3e
	s_branch .Lbg_idx_done
.Lbg_rank:
	v_readlane_b32 s5, v254, 48
	s_cmp_lg_u32 s5, 0
	s_cbranch_scc1 .Lbg_idx_done
	v_readlane_b32 s4, v255, 20
	s_cmp_ge_u32 s4, 64
	s_cbranch_scc1 .Lbg_idx_done
	s_cmp_ge_u32 s4, 26
	s_cbranch_scc1 .LBB0_1015
	s_lshl_b32 s4, s4, 3
	s_add_u32 s98, s4, s88
	s_movk_i32 s99, 0xd0

; __device__ __forceinline__ unsigned xb_add(unsigned* p, unsigned v) { return __hip_atomic_fetch_add(p, v, __ATOMIC_RELAXED, __HIP_MEMORY_SCOPE_AGENT); }
; __device__ __forceinline__ void xcd_barrier_thread0(const XcdBarrier& b) {
;     ...
;         const unsigned old = xb_add(&bar[XB_XSUB(b.x)], 1u);
;         const unsigned gen = old / nloc;
;         if (old + 1u == (gen + 1u) * nloc) {
.LBB0_1036:
	s_or_b64 exec, exec, s[0:1]
	v_cvt_f32_u32_e32 v8, v6
	s_waitcnt vmcnt(0)
	v_readfirstlane_b32 s0, v7
	s_and_b32 s2, s0, 31
	s_add_i32 s3, s90, 1
	s_lshl_b32 s3, s3, 8
	s_or_b32 s2, s2, s3
	v_mov_b32_e32 v20, 0x20180
	v_mov_b32_e32 v21, s2
	ds_write_b32 v20, v21
	v_sub_u32_e32 v7, 0, v6
	v_rcp_iflag_f32_e32 v8, v8
	v_add_u32_e32 v9, s0, v5
	v_mul_f32_e32 v8, 0x4f7ffffe, v8
	v_cvt_u32_f32_e32 v8, v8
	v_mul_lo_u32 v5, v7, v8
	v_mul_hi_u32 v5, v8, v5
	v_add_u32_e32 v5, v8, v5
	v_mul_hi_u32 v5, v9, v5
	v_mul_lo_u32 v7, v5, v6
	v_sub_u32_e32 v7, v9, v7
	v_add_u32_e32 v8, 1, v5
	v_cmp_ge_u32_e32 vcc, v7, v6
	s_nop 1
	v_cndmask_b32_e32 v5, v5, v8, vcc
	v_sub_u32_e32 v8, v7, v6
	v_cndmask_b32_e32 v7, v7, v8, vcc
	v_add_u32_e32 v8, 1, v5
	v_cmp_ge_u32_e32 vcc, v7, v6
	v_add_u32_e32 v7, 1, v9
	s_nop 0
	v_cndmask_b32_e32 v5, v5, v8, vcc
	v_mul_lo_u32 v8, v6, v5
	v_add_u32_e32 v6, v8, v6
	v_cmp_ne_u32_e32 vcc, v7, v6
	s_and_saveexec_b64 s[0:1], vcc
	s_xor_b64 s[0:1], exec, s[0:1]
	s_cbranch_execz .LBB0_1050
	v_readlane_b32 s2, v253, 14
	v_readlane_b32 s3, v253, 15
	s_waitcnt lgkmcnt(0)
	s_nop 3
	buffer_inv sc1
	global_load_dword v4, v3, s[2:3] sc1
	s_waitcnt vmcnt(0)
	v_cmp_eq_u32_e32 vcc, v4, v5
	s_and_saveexec_b64 s[2:3], vcc
	s_cbranch_execz .LBB0_1049
	s_mov_b32 s15, 1
	s_mov_b64 s[8:9], 0
	s_branch .LBB0_1040
